# attention unit prologue de-serialised: tile 1 LDS-DMA issued together with tile 0 before the first wait and barrier (one fewer exposed DMA round trip per unit)
# speedup vs baseline: 1.0031x; 1.0031x over previous
; __device__ __forceinline__ void attn_dense_body(const bf16* Qb, const bf16* __restrict__ Kh, const bf16* __restrict__ Vh, const bf16* __restrict__ Zb, ...
;     ...
;   const TQ* Qw = Qb + (long)(wid * QBLK + r32) * LDQ + hi * 8;
; #pragma unroll
;   for (int d0 = 0; d0 < 8; ++d0) qr[d0] = SQ::tobf(SQ::ld8(Qw + d0 * 16));
;   float negBC;
;   { float ss = 0.f;
; #pragma unroll
;     for (int d0 = 0; d0 < 8; ++d0)
; #pragma unroll
;       for (int e = 0; e < 8; ++e) { const float qv = __uint_as_float((unsigned)(unsigned short)qr[d0][e] << 16); ss = fmaf(qv, qv, ss); }
;     auto rr = __builtin_amdgcn_permlane32_swap(__float_as_uint(ss), __float_as_uint(ss), false, false);
;     ss = __uint_as_float(rr[0]) + __uint_as_float(rr[1]);
;     negBC = -(sqrtf(ss) * kmax * (11.313708498984761f * 1.01f) + 0.07f); }
; __global__ void __launch_bounds__(NTHREADS, 2) mega(Params P) {
;     ...
;                 if (un < 1024) { b = un >> 9; h = (un >> 6) & 7; rowq = b * TB + CTXL + (un & 63) * 256; seq = TB; }
;                 else { const int c = un - 1024; b = c >> 3; h = c & 7; rowq = b * TB; seq = CTXL; }
;                 const size_t qoff = (size_t)rowq * DM + h * 128, koff = (size_t)b * TB * 256 + (h >> 2) * 128;
;                 att::attn_dense_body((const att::bf16*)(Q + qoff), (const att::bf16*)(Kb + koff), (const att::bf16*)(Vb + koff), (const att::bf16*)(ZA + qoff), (att::bf16*)(Q + qoff), seq, (char*)lds, wave, kmax, l3);
.LBB0_116:
	s_and_b32 s16, s15, 7
	s_ashr_i32 s25, s24, 31
	s_lshl_b64 s[24:25], s[24:25], 10
	s_lshl_b32 s16, s16, 7
	s_lshl_b32 s17, s15, 5
	s_or_b32 s24, s24, s16
	s_mul_i32 s16, s14, 0x410000
	s_and_b32 s17, s17, 0x80
	v_mov_b32_e32 v32, v236
	s_or_b32 s40, s16, s17
	s_lshl_b64 s[44:45], s[24:25], 1
	s_add_u32 s24, s8, s44
	v_and_b32_e32 v10, 31, v32
	v_ashrrev_i32_e32 v245, 5, v32
	v_or_b32_e32 v160, s69, v10
	s_addc_u32 s25, s9, s45
	v_lshlrev_b64 v[0:1], 11, v[160:161]
	v_lshlrev_b32_e32 v2, 3, v245
	v_lshl_add_u64 v[0:1], s[24:25], 0, v[0:1]
	v_ashrrev_i32_e32 v3, 31, v2
	v_lshl_add_u64 v[0:1], v[2:3], 1, v[0:1]
	flat_load_dwordx4 v[140:143], v[0:1]
	flat_load_dwordx4 v[136:139], v[0:1] offset:32
	flat_load_dwordx4 v[132:135], v[0:1] offset:64
	flat_load_dwordx4 v[128:131], v[0:1] offset:96
	flat_load_dwordx4 v[124:127], v[0:1] offset:128
	flat_load_dwordx4 v[120:123], v[0:1] offset:160
	flat_load_dwordx4 v[116:119], v[0:1] offset:192
	flat_load_dwordx4 v[112:115], v[0:1] offset:224
	s_mov_b32 s16, 0xf800000
	s_mul_hi_i32 s41, s14, 0x410000
	s_lshl_b64 s[40:41], s[40:41], 1
	s_add_u32 s46, s10, s40
	s_addc_u32 s47, s11, s41
	s_add_u32 s48, s12, s40
	s_addc_u32 s49, s13, s41
	s_add_i32 m0, s90, 0xc000
	v_mov_b32_e32 v146, 0
	s_mov_b32 s54, 0
	v_mov_b32_e32 v58, v146
	v_mov_b32_e32 v59, v146
	v_mov_b32_e32 v60, v146
	v_mov_b32_e32 v61, v146
	v_mov_b32_e32 v62, v146
	v_mov_b32_e32 v63, v146
	s_waitcnt vmcnt(0) lgkmcnt(0)
	v_lshlrev_b32_e32 v0, 16, v140
	v_and_b32_e32 v1, 0xffff0000, v140
	v_fma_f32 v0, v0, v0, 0
	v_lshlrev_b32_e32 v2, 16, v141
	v_fmac_f32_e32 v0, v1, v1
	v_and_b32_e32 v3, 0xffff0000, v141
	v_fmac_f32_e32 v0, v2, v2
	v_lshlrev_b32_e32 v4, 16, v142
	v_fmac_f32_e32 v0, v3, v3
	v_and_b32_e32 v5, 0xffff0000, v142
	v_fmac_f32_e32 v0, v4, v4
	v_lshlrev_b32_e32 v6, 16, v143
	v_fmac_f32_e32 v0, v5, v5
	v_and_b32_e32 v7, 0xffff0000, v143
	v_fmac_f32_e32 v0, v6, v6
	v_lshlrev_b32_e32 v8, 16, v136
	v_fmac_f32_e32 v0, v7, v7
	v_and_b32_e32 v9, 0xffff0000, v136
	v_fmac_f32_e32 v0, v8, v8
	v_lshlrev_b32_e32 v11, 16, v137
	v_fmac_f32_e32 v0, v9, v9
	v_and_b32_e32 v12, 0xffff0000, v137
	v_fmac_f32_e32 v0, v11, v11
	v_lshlrev_b32_e32 v13, 16, v138
	v_fmac_f32_e32 v0, v12, v12
	v_and_b32_e32 v14, 0xffff0000, v138
	v_fmac_f32_e32 v0, v13, v13
	v_lshlrev_b32_e32 v15, 16, v139
	v_fmac_f32_e32 v0, v14, v14
	v_and_b32_e32 v16, 0xffff0000, v139
	v_fmac_f32_e32 v0, v15, v15
	v_lshlrev_b32_e32 v17, 16, v132
	v_fmac_f32_e32 v0, v16, v16
	v_and_b32_e32 v18, 0xffff0000, v132
	v_fmac_f32_e32 v0, v17, v17
	v_lshlrev_b32_e32 v19, 16, v133
	v_fmac_f32_e32 v0, v18, v18
	v_and_b32_e32 v20, 0xffff0000, v133
	v_fmac_f32_e32 v0, v19, v19
	v_lshlrev_b32_e32 v21, 16, v134
	v_fmac_f32_e32 v0, v20, v20
	v_and_b32_e32 v22, 0xffff0000, v134
	v_fmac_f32_e32 v0, v21, v21
	v_lshlrev_b32_e32 v23, 16, v135
	v_fmac_f32_e32 v0, v22, v22
	v_and_b32_e32 v24, 0xffff0000, v135
	v_fmac_f32_e32 v0, v23, v23
	v_lshlrev_b32_e32 v25, 16, v128
	v_fmac_f32_e32 v0, v24, v24
	v_and_b32_e32 v26, 0xffff0000, v128
	v_fmac_f32_e32 v0, v25, v25
	v_lshlrev_b32_e32 v27, 16, v129
	v_fmac_f32_e32 v0, v26, v26
	v_and_b32_e32 v28, 0xffff0000, v129
	v_fmac_f32_e32 v0, v27, v27
	v_lshlrev_b32_e32 v29, 16, v130
	v_fmac_f32_e32 v0, v28, v28
	v_and_b32_e32 v30, 0xffff0000, v130
	v_fmac_f32_e32 v0, v29, v29
	v_lshlrev_b32_e32 v31, 16, v131
	v_fmac_f32_e32 v0, v30, v30
	v_and_b32_e32 v33, 0xffff0000, v131
	v_fmac_f32_e32 v0, v31, v31
	v_lshlrev_b32_e32 v34, 16, v124
	v_fmac_f32_e32 v0, v33, v33
	v_and_b32_e32 v35, 0xffff0000, v124
	v_fmac_f32_e32 v0, v34, v34
	v_lshlrev_b32_e32 v36, 16, v125
	v_fmac_f32_e32 v0, v35, v35
	v_and_b32_e32 v37, 0xffff0000, v125
	v_fmac_f32_e32 v0, v36, v36
	v_lshlrev_b32_e32 v38, 16, v126
	v_fmac_f32_e32 v0, v37, v37
	v_and_b32_e32 v39, 0xffff0000, v126
	v_fmac_f32_e32 v0, v38, v38
	v_lshlrev_b32_e32 v40, 16, v127
	v_fmac_f32_e32 v0, v39, v39
	v_and_b32_e32 v41, 0xffff0000, v127
	v_fmac_f32_e32 v0, v40, v40
	v_lshlrev_b32_e32 v42, 16, v120
	v_fmac_f32_e32 v0, v41, v41
	v_and_b32_e32 v43, 0xffff0000, v120
	v_fmac_f32_e32 v0, v42, v42
	v_lshlrev_b32_e32 v44, 16, v121
	v_fmac_f32_e32 v0, v43, v43
	v_and_b32_e32 v45, 0xffff0000, v121
	v_fmac_f32_e32 v0, v44, v44
	v_lshlrev_b32_e32 v46, 16, v122
	v_fmac_f32_e32 v0, v45, v45
	v_and_b32_e32 v47, 0xffff0000, v122
	v_fmac_f32_e32 v0, v46, v46
	v_lshlrev_b32_e32 v48, 16, v123
	v_fmac_f32_e32 v0, v47, v47
	v_and_b32_e32 v49, 0xffff0000, v123
	v_fmac_f32_e32 v0, v48, v48
	v_lshlrev_b32_e32 v50, 16, v116
	v_fmac_f32_e32 v0, v49, v49
	v_and_b32_e32 v51, 0xffff0000, v116
	v_fmac_f32_e32 v0, v50, v50
	v_lshlrev_b32_e32 v52, 16, v117
	v_fmac_f32_e32 v0, v51, v51
	v_and_b32_e32 v53, 0xffff0000, v117
	v_fmac_f32_e32 v0, v52, v52
	v_lshlrev_b32_e32 v54, 16, v118
	v_fmac_f32_e32 v0, v53, v53
	v_and_b32_e32 v55, 0xffff0000, v118
	v_fmac_f32_e32 v0, v54, v54
	v_lshlrev_b32_e32 v56, 16, v119
	v_fmac_f32_e32 v0, v55, v55
	v_and_b32_e32 v57, 0xffff0000, v119
	v_fmac_f32_e32 v0, v56, v56
	v_fmac_f32_e32 v0, v57, v57
	v_lshlrev_b32_e32 v1, 16, v112
	v_fmac_f32_e32 v0, v1, v1
	v_and_b32_e32 v1, 0xffff0000, v112
	v_fmac_f32_e32 v0, v1, v1
	v_lshlrev_b32_e32 v1, 16, v113
	v_fmac_f32_e32 v0, v1, v1
	v_and_b32_e32 v1, 0xffff0000, v113
	v_fmac_f32_e32 v0, v1, v1
	v_lshlrev_b32_e32 v1, 16, v114
	v_fmac_f32_e32 v0, v1, v1
	v_and_b32_e32 v1, 0xffff0000, v114
	v_fmac_f32_e32 v0, v1, v1
	v_lshlrev_b32_e32 v1, 16, v115
	v_fmac_f32_e32 v0, v1, v1
	v_and_b32_e32 v1, 0xffff0000, v115
	v_fmac_f32_e32 v0, v1, v1
	v_mov_b32_e32 v1, v0
	s_nop 1
	v_permlane32_swap_b32_e32 v0, v1
	v_add_f32_e32 v0, v0, v1
	v_mul_f32_e32 v1, 0x4f800000, v0
	v_cmp_gt_f32_e32 vcc, s16, v0
; __device__ __forceinline__ void partialSM3(f32x16& p0) { for (int r = 0; r < 16; ++r) p0[r] = __builtin_amdgcn_exp2f(p0[r]); }
; __device__ __forceinline__ int v_rd_base2(int lane) { return ((lane & 3) << 3) | (((lane >> 2) & 3) << 6) | (((lane >> 4) & 1) << 5) | (((lane >> 5) & 1) << 11); }
; #define DWAIT() asm volatile("s_waitcnt vmcnt(0)" ::: "memory")
; __device__ __forceinline__ void attn_dense_body(const bf16* Qb, const bf16* __restrict__ Kh, const bf16* __restrict__ Vh, const bf16* __restrict__ Zb, ...
;     ...
;     negBC = -(sqrtf(ss) * kmax * (11.313708498984761f * 1.01f) + 0.07f); }
;   f32x16 cinit; for (int r = 0; r < 16; ++r) cinit[r] = negBC;
;   const int vb0 = (int)(uintptr_t)V_lds + v_rd_base2(lane);
;   int koff0, koff1, voff0, voff1;
;   { const int rk0 = 8 * wid + (lane >> 4), rk1 = rk0 + 4; koff0 = rk0 * (LDK * 2) + (((lane & 15) ^ (rk0 & 15)) << 4); koff1 = rk1 * (LDK * 2) + (((lane & 15) ^ (rk1 & 15)) << 4);
;     const int st0 = 4 * wid + (lane >> 5), st1 = st0 + 2, q8 = (lane & 31) >> 2;
;     const int kk0 = ((st0 >> 2) << 3) | q8, kk1 = ((st1 >> 2) << 3) | q8;
;     const int ky0 = (kk0 & ~0xC) | ((kk0 & 4) << 1) | ((kk0 & 8) >> 1), ky1 = (kk1 & ~0xC) | ((kk1 & 4) << 1) | ((kk1 & 8) >> 1);
;     voff0 = ky0 * (LDK * 2) + ((st0 & 3) * 32 + (lane & 3) * 8) * 2; voff1 = ky1 * (LDK * 2) + ((st1 & 3) * 32 + (lane & 3) * 8) * 2; }
;     ...
;   f32x16 pA0, pA1, pB0, pB1; bf16x8 pa0, pa1, pa2, pa3; const int NT = seq / KVBLK;
;   SDMA(0, 0); DWAIT(); __syncthreads();
;   SDMA(1, KVBLK);
;   qkt3(pA0, pA1, K_lds, qr, r32, hi, cinit); partialSM3(pA0);
;   for (int r = 0; r < 16; ++r) pA1[r] = __builtin_amdgcn_exp2f(pA1[r]);
;   DWAIT(); __syncthreads();
	v_ashrrev_i32_e32 v43, 4, v32
	v_bfe_u32 v48, v32, 2, 2
	v_cndmask_b32_e32 v0, v0, v1, vcc
	v_sqrt_f32_e32 v1, v0
	v_lshlrev_b32_e32 v42, 4, v32
	v_lshlrev_b32_e32 v52, 4, v245
	v_lshlrev_b32_e32 v53, 8, v10
	v_add_u32_e32 v2, -1, v1
	v_fma_f32 v3, -v2, v1, v0
	v_cmp_ge_f32_e64 s[40:41], 0, v3
	v_add_u32_e32 v3, 1, v1
	v_and_b32_e32 v54, 0xf0, v42
	v_cndmask_b32_e64 v2, v1, v2, s[40:41]
	v_fma_f32 v1, -v3, v1, v0
	v_cmp_lt_f32_e64 s[40:41], 0, v1
	v_xad_u32 v157, v54, v52, v53
	s_movk_i32 s16, 0xc0
	v_cndmask_b32_e64 v1, v2, v3, s[40:41]
	v_mul_f32_e32 v2, 0x37800000, v1
	v_cndmask_b32_e32 v1, v1, v2, vcc
	v_cmp_class_f32_e32 vcc, v0, v233
	v_mov_b32_e32 v55, v146
	v_mov_b32_e32 v56, v146
	v_cndmask_b32_e32 v0, v1, v0, vcc
	v_mul_f32_e32 v0, v145, v0
	v_fmamk_f32 v0, v0, 0x4136d45c, v234
	v_xor_b32_e32 v64, 0x80000000, v0
	v_lshlrev_b32_e32 v0, 3, v32
	v_and_b32_e32 v33, 24, v0
	v_add_u32_e32 v0, s88, v43
	v_xor_b32_e32 v2, v0, v32
	v_add_u32_e32 v1, 4, v0
	v_lshlrev_b32_e32 v2, 4, v2
	v_and_b32_e32 v44, 0xf0, v2
	v_xor_b32_e32 v2, v1, v32
	v_lshlrev_b32_e32 v2, 4, v2
	v_and_b32_e32 v45, 0xf0, v2
	v_lshl_or_b32 v2, v1, 9, v45
	v_add_u32_e32 v1, s89, v245
	v_add_u32_e32 v3, 2, v1
	v_lshlrev_b32_e32 v4, 1, v1
	v_and_b32_e32 v46, -16, v4
	v_lshlrev_b32_e32 v4, 1, v3
	v_and_b32_e32 v47, -16, v4
	v_lshrrev_b32_e32 v4, 1, v32
	v_and_b32_e32 v51, 4, v3
	v_and_b32_e32 v49, 8, v4
	v_and_b32_e32 v50, 4, v1
	v_or_b32_e32 v4, v51, v47
	v_or_b32_e32 v1, v50, v46
	v_or3_b32 v5, v4, v48, v49
	v_and_or_b32 v4, v32, s93, v33
	v_or3_b32 v1, v1, v48, v49
	v_lshlrev_b32_e32 v4, 1, v4
	v_lshl_or_b32 v4, v1, 9, v4
	v_lshlrev_b32_e32 v1, 5, v3
	v_and_or_b32 v1, v1, s93, v33
	v_lshl_or_b32 v0, v0, 9, v44
	v_lshlrev_b32_e32 v1, 1, v1
	v_lshl_or_b32 v6, v5, 9, v1
	v_ashrrev_i32_e32 v1, 31, v0
	v_lshl_add_u64 v[8:9], s[46:47], 0, v[0:1]
	v_ashrrev_i32_e32 v3, 31, v2
	global_load_lds_dwordx4 v[8:9], off
	v_lshl_add_u64 v[8:9], s[46:47], 0, v[2:3]
	s_add_i32 m0, s90, 0xc400
	v_ashrrev_i32_e32 v5, 31, v4
	global_load_lds_dwordx4 v[8:9], off
	v_lshl_add_u64 v[8:9], s[48:49], 0, v[4:5]
	s_mov_b32 m0, s90
	v_ashrrev_i32_e32 v7, 31, v6
	global_load_lds_dwordx4 v[8:9], off
	s_add_i32 m0, s90, 0x400
	s_add_u32 s40, s46, 0x8000
	s_addc_u32 s41, s47, 0
	v_lshl_add_u64 v[8:9], s[48:49], 0, v[6:7]
	s_add_u32 s46, s48, 0x8000
	global_load_lds_dwordx4 v[8:9], off
	s_addc_u32 s47, s49, 0
	v_lshl_add_u64 v[0:1], s[40:41], 0, v[0:1]
	s_add_i32 m0, s90, 0x10000
	s_nop 0
	global_load_lds_dwordx4 v[0:1], off
	v_lshl_add_u64 v[0:1], s[40:41], 0, v[2:3]
	s_add_i32 m0, s90, 0x10400
	s_nop 0
	global_load_lds_dwordx4 v[0:1], off
	v_lshl_add_u64 v[0:1], s[46:47], 0, v[4:5]
	s_add_i32 m0, s90, 0x4000
	s_nop 0
	global_load_lds_dwordx4 v[0:1], off
	v_lshl_add_u64 v[0:1], s[46:47], 0, v[6:7]
	s_add_i32 m0, s90, 0x4400
	s_nop 0
	global_load_lds_dwordx4 v[0:1], off
	s_waitcnt vmcnt(0)
	s_waitcnt vmcnt(0) lgkmcnt(0)
	s_barrier
	v_mov_b32_e32 v65, v64
	v_add_u32_e32 v4, 0, v157
	v_mov_b32_e32 v66, v64
	ds_read_b128 v[0:3], v4 offset:49152
	ds_read_b128 v[34:37], v4 offset:57344
	v_mov_b32_e32 v67, v64
	v_mov_b32_e32 v68, v64
	v_mov_b32_e32 v69, v64
	v_mov_b32_e32 v70, v64
	v_mov_b32_e32 v71, v64
	v_mov_b32_e32 v72, v64
	v_mov_b32_e32 v73, v64
	v_mov_b32_e32 v74, v64
	v_mov_b32_e32 v75, v64
	v_mov_b32_e32 v76, v64
	v_mov_b32_e32 v77, v64
	v_mov_b32_e32 v78, v64
	v_mov_b32_e32 v79, v64
	s_cmp_lg_u32 0, -1
	s_mov_b32 s46, 1
	s_waitcnt lgkmcnt(0)
	v_mfma_f32_32x32x16_bf16 v[16:31], v[0:3], v[140:143], v[64:79]
	s_mov_b32 s47, 2
	s_mov_b32 s48, 2
	v_mov_b32_e32 v57, v146
	v_mfma_f32_32x32x16_bf16 v[0:15], v[34:37], v[140:143], v[64:79]
	v_add_u32_e32 v34, 32, v52
	v_xad_u32 v177, v34, v54, v53
	v_add_u32_e32 v38, 0, v177
	ds_read_b128 v[34:37], v38 offset:49152
	ds_read_b128 v[38:41], v38 offset:57344
	s_waitcnt lgkmcnt(0)
	v_mfma_f32_32x32x16_bf16 v[16:31], v[34:37], v[136:139], v[16:31]
	v_add_u32_e32 v34, 64, v52
	v_xad_u32 v175, v34, v54, v53
	v_mfma_f32_32x32x16_bf16 v[0:15], v[38:41], v[136:139], v[0:15]
	v_add_u32_e32 v38, 0, v175
	ds_read_b128 v[34:37], v38 offset:49152
	ds_read_b128 v[38:41], v38 offset:57344
	s_waitcnt lgkmcnt(0)
	v_mfma_f32_32x32x16_bf16 v[16:31], v[34:37], v[132:135], v[16:31]
	v_add_u32_e32 v34, 0x60, v52
	v_xad_u32 v173, v34, v54, v53
	v_mfma_f32_32x32x16_bf16 v[0:15], v[38:41], v[132:135], v[0:15]
	v_add_u32_e32 v38, 0, v173
	ds_read_b128 v[34:37], v38 offset:49152
	ds_read_b128 v[38:41], v38 offset:57344
	s_waitcnt lgkmcnt(0)
	v_mfma_f32_32x32x16_bf16 v[16:31], v[34:37], v[128:131], v[16:31]
	v_add_u32_e32 v34, 0x80, v52
	v_xad_u32 v171, v34, v54, v53
	v_mfma_f32_32x32x16_bf16 v[0:15], v[38:41], v[128:131], v[0:15]
	v_add_u32_e32 v38, 0, v171
	ds_read_b128 v[34:37], v38 offset:49152
	ds_read_b128 v[38:41], v38 offset:57344
	s_waitcnt lgkmcnt(0)
	v_mfma_f32_32x32x16_bf16 v[16:31], v[34:37], v[124:127], v[16:31]
	v_add_u32_e32 v34, 0xa0, v52
	v_xad_u32 v169, v34, v54, v53
	v_mfma_f32_32x32x16_bf16 v[0:15], v[38:41], v[124:127], v[0:15]
	v_add_u32_e32 v38, 0, v169
	ds_read_b128 v[34:37], v38 offset:49152
	ds_read_b128 v[38:41], v38 offset:57344
	s_waitcnt lgkmcnt(0)
	v_mfma_f32_32x32x16_bf16 v[16:31], v[34:37], v[120:123], v[16:31]
	v_add_u32_e32 v34, 0xc0, v52
	v_xad_u32 v167, v34, v54, v53
	v_mfma_f32_32x32x16_bf16 v[0:15], v[38:41], v[120:123], v[0:15]
	v_add_u32_e32 v38, 0, v167
	ds_read_b128 v[34:37], v38 offset:49152
	ds_read_b128 v[38:41], v38 offset:57344
	s_waitcnt lgkmcnt(0)
	v_mfma_f32_32x32x16_bf16 v[16:31], v[34:37], v[116:119], v[16:31]
	v_add_u32_e32 v34, 0xe0, v52
	v_xad_u32 v159, v34, v54, v53
	v_mov_b32_e32 v52, v146
	v_mov_b32_e32 v53, v146
	v_mov_b32_e32 v54, v146
	v_mfma_f32_32x32x16_bf16 v[0:15], v[38:41], v[116:119], v[0:15]
	v_add_u32_e32 v38, 0, v159
	ds_read_b128 v[34:37], v38 offset:49152
	ds_read_b128 v[38:41], v38 offset:57344
	s_waitcnt vmcnt(0)
	s_waitcnt vmcnt(0) lgkmcnt(0)
	s_barrier
; __device__ __forceinline__ void partialSM3(f32x16& p0) { for (int r = 0; r < 16; ++r) p0[r] = __builtin_amdgcn_exp2f(p0[r]); }
; __device__ __forceinline__ int v_rd_base2(int lane) { return ((lane & 3) << 3) | (((lane >> 2) & 3) << 6) | (((lane >> 4) & 1) << 5) | (((lane >> 5) & 1) << 11); }
; #define DWAIT() asm volatile("s_waitcnt vmcnt(0)" ::: "memory")
; __device__ __forceinline__ void attn_dense_body(const bf16* Qb, const bf16* __restrict__ Kh, const bf16* __restrict__ Vh, const bf16* __restrict__ Zb, ...
;     ...
;   const int vb0 = (int)(uintptr_t)V_lds + v_rd_base2(lane);
;   int koff0, koff1, voff0, voff1;
;   { const int rk0 = 8 * wid + (lane >> 4), rk1 = rk0 + 4; koff0 = rk0 * (LDK * 2) + (((lane & 15) ^ (rk0 & 15)) << 4); koff1 = rk1 * (LDK * 2) + (((lane & 15) ^ (rk1 & 15)) << 4);
;     const int st0 = 4 * wid + (lane >> 5), st1 = st0 + 2, q8 = (lane & 31) >> 2;
;     const int kk0 = ((st0 >> 2) << 3) | q8, kk1 = ((st1 >> 2) << 3) | q8;
;     const int ky0 = (kk0 & ~0xC) | ((kk0 & 4) << 1) | ((kk0 & 8) >> 1), ky1 = (kk1 & ~0xC) | ((kk1 & 4) << 1) | ((kk1 & 8) >> 1);
;     voff0 = ky0 * (LDK * 2) + ((st0 & 3) * 32 + (lane & 3) * 8) * 2; voff1 = ky1 * (LDK * 2) + ((st1 & 3) * 32 + (lane & 3) * 8) * 2; }
;     ...
;   f32x16 pA0, pA1, pB0, pB1; bf16x8 pa0, pa1, pa2, pa3; const int NT = seq / KVBLK;
;   SDMA(0, 0); DWAIT(); __syncthreads();
;   SDMA(1, KVBLK);
;   qkt3(pA0, pA1, K_lds, qr, r32, hi, cinit); partialSM3(pA0);
;   for (int r = 0; r < 16; ++r) pA1[r] = __builtin_amdgcn_exp2f(pA1[r]);
;   DWAIT(); __syncthreads();
;   int sP = 0, sC = 1, sN = 2;
	v_mfma_f32_32x32x16_bf16 v[0:15], v[38:41], v[112:115], v[0:15]
	v_mov_b32_e32 v38, v146
	v_mov_b32_e32 v39, v146
	v_mov_b32_e32 v40, v146
	v_mov_b32_e32 v41, v146
	s_nop 7
	v_exp_f32_e32 v168, v0
	v_mfma_f32_32x32x16_bf16 v[16:31], v[34:37], v[112:115], v[16:31]
	v_exp_f32_e32 v156, v1
	v_or_b32_e32 v0, v47, v49
	v_add_u16_e32 v1, 2, v245
	v_lshlrev_b32_e32 v34, 1, v32
	v_or3_b32 v0, v0, v51, v48
	v_and_b32_e32 v1, 3, v1
	v_and_b32_e32 v35, 32, v34
	v_lshlrev_b32_e32 v32, 6, v32
	v_exp_f32_e32 v158, v2
	v_lshlrev_b32_e32 v0, 9, v0
	v_lshlrev_b32_e32 v1, 6, v1
	v_and_b32_e32 v2, 48, v42
	v_and_or_b32 v35, v42, s16, v35
	v_and_b32_e32 v32, 0x800, v32
	v_or3_b32 v148, v0, v1, v2
	v_or_b32_e32 v0, v46, v49
	v_or3_b32 v32, v35, v32, v33
	s_cselect_b32 s16, 0, 0
	s_lshl_b32 s15, s15, 6
	v_or3_b32 v0, v0, v50, v48
	v_add_u32_e32 v147, s16, v32
	v_exp_f32_e32 v179, v16
	v_exp_f32_e32 v170, v17
	v_exp_f32_e32 v172, v18
	v_exp_f32_e32 v174, v19
	v_exp_f32_e32 v184, v20
	v_exp_f32_e32 v186, v21
	v_exp_f32_e32 v188, v22
	v_exp_f32_e32 v190, v23
	v_exp_f32_e32 v206, v24
	v_exp_f32_e32 v200, v25
	v_exp_f32_e32 v202, v26
	v_exp_f32_e32 v204, v27
	v_exp_f32_e32 v216, v28
	v_exp_f32_e32 v218, v29
	v_exp_f32_e32 v220, v30
	v_exp_f32_e32 v222, v31
	v_exp_f32_e32 v166, v3
	v_exp_f32_e32 v176, v4
	v_exp_f32_e32 v178, v5
	v_exp_f32_e32 v180, v6
	v_exp_f32_e32 v182, v7
	v_exp_f32_e32 v198, v8
	v_exp_f32_e32 v196, v9
	v_exp_f32_e32 v192, v10
	v_exp_f32_e32 v194, v11
	v_exp_f32_e32 v208, v12
	v_exp_f32_e32 v210, v13
	v_exp_f32_e32 v212, v14
	v_exp_f32_e32 v214, v15
	s_mul_hi_i32 s16, s14, 0x820000
	s_mul_i32 s14, s14, 0x820000
	s_and_b32 s15, s15, 0x100
	v_lshlrev_b32_e32 v0, 9, v0
	v_and_b32_e32 v1, 0xc0, v34
	s_or_b32 s14, s14, s15
	v_or3_b32 v150, v0, v1, v2
	v_lshlrev_b32_e32 v0, 9, v43
	s_add_u32 s40, s42, s14
	v_add3_u32 v152, s92, v0, v45
	v_add3_u32 v154, s63, v0, v44
	v_ashrrev_i32_e32 v149, 31, v148
	s_addc_u32 s41, s43, s16
	v_ashrrev_i32_e32 v151, 31, v150
	v_ashrrev_i32_e32 v153, 31, v152
	v_ashrrev_i32_e32 v155, 31, v154
	v_mov_b32_e32 v0, 0
	v_mov_b32_e32 v1, v146
	v_mov_b32_e32 v2, v146
	v_mov_b32_e32 v3, v146
	v_mov_b32_e32 v4, v146
	v_mov_b32_e32 v5, v146
	v_mov_b32_e32 v6, v146
	v_mov_b32_e32 v7, v146
	v_mov_b32_e32 v8, v146
	v_mov_b32_e32 v9, v146
	v_mov_b32_e32 v10, v146
	v_mov_b32_e32 v11, v146
	v_mov_b32_e32 v12, v146
	v_mov_b32_e32 v13, v146
	v_mov_b32_e32 v14, v146
	v_mov_b32_e32 v15, v146
	v_mov_b32_e32 v16, 0
	v_mov_b32_e32 v17, v146
	v_mov_b32_e32 v18, v146
	v_mov_b32_e32 v19, v146
	v_mov_b32_e32 v20, v146
	v_mov_b32_e32 v21, v146
	v_mov_b32_e32 v22, v146
	v_mov_b32_e32 v23, v146
	v_mov_b32_e32 v24, v146
	v_mov_b32_e32 v25, v146
	v_mov_b32_e32 v26, v146
	v_mov_b32_e32 v27, v146
	v_mov_b32_e32 v28, v146
	v_mov_b32_e32 v29, v146
	v_mov_b32_e32 v30, v146
	v_mov_b32_e32 v31, v146
	v_mov_b32_e32 v32, 0
	v_mov_b32_e32 v33, v146
	v_mov_b32_e32 v34, v146
	v_mov_b32_e32 v35, v146
	v_mov_b32_e32 v36, v146
	v_mov_b32_e32 v37, v146
	v_mov_b32_e32 v42, v146
	v_mov_b32_e32 v43, v146
	v_mov_b32_e32 v44, v146
	v_mov_b32_e32 v45, v146
	v_mov_b32_e32 v46, v146
	v_mov_b32_e32 v47, v146
	v_mov_b32_e32 v48, 0
	v_mov_b32_e32 v49, v146
	v_mov_b32_e32 v50, v146
	v_mov_b32_e32 v51, v146
	s_add_u32 s84, s40, s58
	s_addc_u32 s85, s41, s59
	s_add_u32 s40, s40, s70
	s_addc_u32 s41, s41, s71
